# v66 + search stagnation guard only on the every-4th bisection iteration (out of line) + early L1 invalidate in the P4 row-statistics exchange
# baseline (speedup 1.0000x reference)
.LBB0_1533:
	s_nop 1
	v_add_u32_dpp v7, v7, v7 quad_perm:[1,0,3,2] row_mask:0xf bank_mask:0xf bound_ctrl:1
	s_nop 1
	v_add_u32_dpp v7, v7, v7 quad_perm:[2,3,0,1] row_mask:0xf bank_mask:0xf bound_ctrl:1
	s_nop 1
	v_add_u32_dpp v7, v7, v7 row_half_mirror row_mask:0xf bank_mask:0xf bound_ctrl:1
	s_nop 1
	v_add_u32_dpp v7, v7, v7 row_mirror row_mask:0xf bank_mask:0xf bound_ctrl:1
	s_nop 1
	v_add_u32_dpp v7, v7, v7 row_bcast:15 row_mask:0xa bank_mask:0xf
	s_nop 0
	v_readlane_b32 s50, v7, 31
	v_readlane_b32 s51, v7, 63
	s_nop 1
	v_mov_b32_e32 v7, s51
	v_mov_b32_e32 v8, s50
	v_cndmask_b32_e64 v8, v7, v8, s[6:7]
	v_cmp_lt_i32_e64 s[82:83], s33, v8
	v_cmp_eq_u32_e64 s[84:85], s33, v8
	v_cvt_f32_i32_e32 v8, v8
	s_andn2_b64 s[84:85], s[84:85], s[72:73]
	s_nop 0
	v_cndmask_b32_e64 v6, v6, v0, s[84:85]
	s_or_b64 s[84:85], s[84:85], s[72:73]
	s_andn2_b64 s[86:87], s[82:83], s[84:85]
	s_or_b64 s[88:89], s[82:83], s[84:85]
	s_andn2_b64 s[88:89], exec, s[88:89]
	v_cndmask_b32_e64 v4, v4, v0, s[86:87]
	v_cndmask_b32_e64 v3, v3, v8, s[86:87]
	v_cndmask_b32_e64 v5, v5, v0, s[88:89]
	v_cndmask_b32_e64 v2, v2, v8, s[88:89]
	s_or_b64 s[78:79], s[78:79], s[86:87]
	s_or_b64 s[76:77], s[76:77], s[88:89]
	s_and_b64 s[90:91], s[78:79], s[76:77]
	v_sub_f32_e32 v9, v3, v2
	v_rcp_f32_e32 v9, v9
	v_add_f32_e32 v10, 0xc3800000, v3
	s_and_b32 s98, s58, 3
	s_cmp_lg_u32 s98, 3
	s_cbranch_scc0 .Lbis0
	v_mul_f32_e32 v9, v10, v9
	v_max_f32_e32 v9, 0x3ca3d70a, v9
	v_min_f32_e32 v9, 0x3f7ae148, v9
	v_sub_f32_e32 v10, v5, v4
	v_fma_f32 v10, v10, v9, v4
	s_mov_b64 s[100:101], 0
.Lbisret0:
	v_cndmask_b32_e64 v11, -v1, v1, s[82:83]
	v_add_f32_e32 v11, v0, v11
	v_cndmask_b32_e64 v10, v11, v10, s[90:91]
	v_add_f32_e32 v11, v1, v1
	s_or_b64 s[98:99], s[90:91], s[84:85]
	s_andn2_b64 s[98:99], exec, s[98:99]
	v_cndmask_b32_e64 v1, v1, v11, s[98:99]
	v_cndmask_b32_e64 v6, v6, v4, s[100:101]
	s_or_b64 s[72:73], s[84:85], s[100:101]
	s_mov_b32 s98, 0x437f0000
	v_cmp_eq_f32_e64 s[82:83], s98, v8
	s_andn2_b64 s[82:83], s[82:83], s[72:73]
	s_cmp_lg_u64 s[82:83], 0
	s_cbranch_scc1 .Lwalk0

.Lbis0:
	v_mul_f32_e32 v10, 0.5, v5
	v_fmac_f32_e32 v10, 0.5, v4
	v_cmp_ngt_f32_e32 vcc, v10, v4
	v_cmp_nlt_f32_e64 s[100:101], v10, v5
	s_or_b64 s[100:101], vcc, s[100:101]
	s_and_b64 s[100:101], s[100:101], s[90:91]
	s_andn2_b64 s[100:101], s[100:101], s[84:85]
	s_branch .Lbisret0

.LBB0_2136:
	s_nop 1
	v_add_u32_dpp v7, v7, v7 quad_perm:[1,0,3,2] row_mask:0xf bank_mask:0xf bound_ctrl:1
	s_nop 1
	v_add_u32_dpp v7, v7, v7 quad_perm:[2,3,0,1] row_mask:0xf bank_mask:0xf bound_ctrl:1
	s_nop 1
	v_add_u32_dpp v7, v7, v7 row_half_mirror row_mask:0xf bank_mask:0xf bound_ctrl:1
	s_nop 1
	v_add_u32_dpp v7, v7, v7 row_mirror row_mask:0xf bank_mask:0xf bound_ctrl:1
	s_nop 1
	v_add_u32_dpp v7, v7, v7 row_bcast:15 row_mask:0xa bank_mask:0xf
	s_nop 0
	v_readlane_b32 s0, v7, 31
	v_readlane_b32 s1, v7, 63
	s_nop 1
	v_mov_b32_e32 v7, s1
	v_mov_b32_e32 v8, s0
	v_cndmask_b32_e64 v8, v7, v8, s[8:9]
	v_cmp_lt_i32_e64 s[82:83], s33, v8
	v_cmp_eq_u32_e64 s[84:85], s33, v8
	v_cvt_f32_i32_e32 v8, v8
	s_andn2_b64 s[84:85], s[84:85], s[74:75]
	s_nop 0
	v_cndmask_b32_e64 v6, v6, v0, s[84:85]
	s_or_b64 s[84:85], s[84:85], s[74:75]
	s_andn2_b64 s[86:87], s[82:83], s[84:85]
	s_or_b64 s[88:89], s[82:83], s[84:85]
	s_andn2_b64 s[88:89], exec, s[88:89]
	v_cndmask_b32_e64 v4, v4, v0, s[86:87]
	v_cndmask_b32_e64 v3, v3, v8, s[86:87]
	v_cndmask_b32_e64 v5, v5, v0, s[88:89]
	v_cndmask_b32_e64 v2, v2, v8, s[88:89]
	s_or_b64 s[80:81], s[80:81], s[86:87]
	s_or_b64 s[78:79], s[78:79], s[88:89]
	s_and_b64 s[90:91], s[80:81], s[78:79]
	v_sub_f32_e32 v9, v3, v2
	v_rcp_f32_e32 v9, v9
	v_add_f32_e32 v10, 0xc3800000, v3
	s_and_b32 s98, s60, 3
	s_cmp_lg_u32 s98, 3
	s_cbranch_scc0 .Lbis1
	v_mul_f32_e32 v9, v10, v9
	v_max_f32_e32 v9, 0x3ca3d70a, v9
	v_min_f32_e32 v9, 0x3f7ae148, v9
	v_sub_f32_e32 v10, v5, v4
	v_fma_f32 v10, v10, v9, v4
	s_mov_b64 s[100:101], 0
.Lbisret1:
	v_cndmask_b32_e64 v11, -v1, v1, s[82:83]
	v_add_f32_e32 v11, v0, v11
	v_cndmask_b32_e64 v10, v11, v10, s[90:91]
	v_add_f32_e32 v11, v1, v1
	s_or_b64 s[98:99], s[90:91], s[84:85]
	s_andn2_b64 s[98:99], exec, s[98:99]
	v_cndmask_b32_e64 v1, v1, v11, s[98:99]
	v_cndmask_b32_e64 v6, v6, v4, s[100:101]
	s_or_b64 s[74:75], s[84:85], s[100:101]
	s_mov_b32 s98, 0x437f0000
	v_cmp_eq_f32_e64 s[82:83], s98, v8
	s_andn2_b64 s[82:83], s[82:83], s[74:75]
	s_cmp_lg_u64 s[82:83], 0
	s_cbranch_scc1 .Lwalk1
